# P3 head loop: conv-tap staging loads for the next head issued one head ahead (held in 3 VGPRs); head top only waits and writes them to LDS
# speedup vs baseline: 1.0106x; 1.0010x over previous
.LBB0_191:
	v_mov_b32_e32 v36, v35
	s_lshl_b32 s56, s31, 7
	s_cmp_lg_u32 s31, 0
	s_cbranch_scc1 .Lp3_tap_have
	s_mov_b32 s34, 0
	v_and_b32_e32 v253, 0x7f, v36
	v_bfe_u32 v248, v36, 7, 2
	v_mul_u32_u24_e32 v248, 0x600, v248
	v_add3_u32 v253, v253, v248, s34
	v_lshlrev_b32_e32 v253, 2, v253
	v_add_u32_e32 v249, 0x1000, v253
	global_load_dword v250, v253, s[14:15]
	global_load_dword v251, v253, s[14:15] offset:2048
	global_load_dword v252, v249, s[14:15]
.Lp3_tap_have:
	s_waitcnt vmcnt(0)
	v_lshl_add_u32 v0, v36, 2, s86
	ds_write_b32 v0, v250
	ds_write_b32 v0, v251 offset:2048
	ds_write_b32 v0, v252 offset:4096
.LBB0_199:
	v_ashrrev_i32_e32 v29, 3, v36
	s_lshl_b32 s74, s31, 6
	v_add_lshl_u32 v0, v29, s74, 2
	s_lshl_b32 s34, s31, 8
	s_waitcnt lgkmcnt(0)
	s_barrier
	s_waitcnt vmcnt(0)
	s_cmp_ge_u32 s31, 3
	s_cbranch_scc1 .Lp3_tap_skip
	s_add_u32 s35, s56, 0x80
	v_and_b32_e32 v253, 0x7f, v36
	v_bfe_u32 v248, v36, 7, 2
	v_mul_u32_u24_e32 v248, 0x600, v248
	v_add3_u32 v253, v253, v248, s35
	v_lshlrev_b32_e32 v253, 2, v253
	v_add_u32_e32 v249, 0x1000, v253
	global_load_dword v250, v253, s[14:15]
	global_load_dword v251, v253, s[14:15] offset:2048
	global_load_dword v252, v249, s[14:15]
.Lp3_tap_skip:
	v_add_u32_e32 v1, s84, v0
	v_add_u32_e32 v0, 0, v0
	s_add_i32 s35, s84, s34
	v_add_u32_e32 v0, 0x1cc00, v0
	v_mov_b32_e32 v3, s35
	ds_read_b32 v31, v1
	ds_read_b32 v26, v0
	ds_read_b32 v37, v3 offset:252
	v_and_b32_e32 v27, 7, v36
	v_lshlrev_b32_e32 v30, 4, v27
	v_or_b32_e32 v2, s56, v30
	v_add_u32_e32 v6, s30, v29
	v_lshlrev_b32_e32 v196, 1, v2
	v_mov_b32_e32 v2, 0
	v_lshl_add_u32 v28, v27, 6, s86
	v_lshl_add_u64 v[0:1], s[62:63], 0, v[196:197]
	v_cmp_lt_i32_e64 s[56:57], -1, v6
	v_mov_b32_e32 v3, 0
	v_mov_b32_e32 v14, 0
	v_mov_b32_e32 v15, 0
	v_mov_b32_e32 v20, 0
	v_mov_b32_e32 v21, v2
	v_mov_b32_e32 v16, v2
	v_mov_b32_e32 v17, v2
	v_mov_b32_e32 v18, v2
	v_mov_b32_e32 v19, v2
	v_mov_b32_e32 v8, v2
	v_mov_b32_e32 v9, v2
	v_mov_b32_e32 v10, v2
	v_mov_b32_e32 v11, v2
	v_mov_b32_e32 v12, v2
	v_mov_b32_e32 v13, v2
	v_mov_b32_e32 v22, 0
	v_mov_b32_e32 v23, 0
	s_and_saveexec_b64 s[8:9], s[56:57]
	s_cbranch_execz .LBB0_201
	v_mov_b32_e32 v7, v197
	v_lshl_add_u64 v[2:3], s[12:13], 0, v[6:7]
	v_mad_u64_u32 v[8:9], s[52:53], v2, s91, v[0:1]
	v_mad_i32_i24 v9, v3, s91, v9
	ds_read_b128 v[14:17], v28
	ds_read_b128 v[22:25], v28 offset:16
	ds_read_b128 v[42:45], v28 offset:32
	ds_read_b128 v[46:49], v28 offset:48
	v_lshlrev_b32_e32 v12, 16, v116
	v_and_b32_e32 v13, 0xffff0000, v116
	v_lshlrev_b32_e32 v8, 16, v117
	v_and_b32_e32 v9, 0xffff0000, v117
	s_waitcnt lgkmcnt(3)
	v_pk_fma_f32 v[20:21], v[16:17], v[8:9], 0 op_sel_hi:[1,1,0]
	v_lshlrev_b32_e32 v8, 16, v118
	v_and_b32_e32 v9, 0xffff0000, v118
	s_waitcnt lgkmcnt(2)
	v_pk_fma_f32 v[16:17], v[22:23], v[8:9], 0 op_sel_hi:[1,1,0]
	v_lshlrev_b32_e32 v8, 16, v119
	v_and_b32_e32 v9, 0xffff0000, v119
	v_pk_fma_f32 v[18:19], v[24:25], v[8:9], 0 op_sel_hi:[1,1,0]
	v_lshlrev_b32_e32 v8, 16, v120
	v_and_b32_e32 v9, 0xffff0000, v120
	v_lshlrev_b32_e32 v2, 16, v121
	v_and_b32_e32 v3, 0xffff0000, v121
	s_waitcnt lgkmcnt(1)
	v_pk_fma_f32 v[10:11], v[44:45], v[2:3], 0 op_sel_hi:[1,1,0]
	v_lshlrev_b32_e32 v2, 16, v122
	v_and_b32_e32 v3, 0xffff0000, v122
	v_pk_fma_f32 v[14:15], v[14:15], v[12:13], 0 op_sel_hi:[1,1,0]
	s_waitcnt lgkmcnt(0)
	v_pk_fma_f32 v[12:13], v[46:47], v[2:3], 0 op_sel_hi:[1,1,0]
	v_lshlrev_b32_e32 v2, 16, v123
	v_and_b32_e32 v3, 0xffff0000, v123
	v_pk_fma_f32 v[2:3], v[48:49], v[2:3], 0 op_sel_hi:[1,1,0]
	v_pk_fma_f32 v[8:9], v[42:43], v[8:9], 0 op_sel_hi:[1,1,0]
	v_mov_b32_e32 v22, v2
	v_mov_b32_e32 v23, v3
